# P7 XN2 stores sc1 nt, on top of v102
# baseline (speedup 1.0000x reference)
.LBB0_807:
	s_ashr_i32 s7, s6, 31
	s_lshl_b64 s[0:1], s[6:7], 6
	s_waitcnt lgkmcnt(0)
	v_lshl_add_u64 v[16:17], v[24:25], 0, s[0:1]
	global_load_dwordx4 v[30:33], v[16:17], off
	s_add_i32 s12, s3, s6
	s_cmp_lt_i32 s12, 0x8000
	s_cselect_b32 s0, s12, s6
	s_ashr_i32 s1, s0, 31
	s_lshl_b64 s[20:21], s[0:1], 6
	s_lshl_b64 s[14:15], s[0:1], 11
	s_lshl_b64 s[0:1], s[0:1], 2
	s_add_u32 s16, s30, s0
	s_addc_u32 s17, s31, s1
	s_lshl_b64 s[0:1], s[6:7], 11
	v_lshl_add_u64 v[28:29], v[22:23], 0, s[0:1]
	global_load_dwordx2 v[34:35], v[28:29], off offset:1536 nt
	v_lshl_add_u64 v[16:17], v[26:27], 0, s[0:1]
	s_lshl_b64 s[0:1], s[6:7], 2
	s_add_u32 s0, s30, s0
	s_addc_u32 s1, s31, s1
	global_load_dwordx2 v[36:37], v[16:17], off offset:512 nt
	global_load_dwordx2 v[38:39], v[28:29], off offset:512 nt
	global_load_dwordx2 v[40:41], v[16:17], off offset:1024 nt
	global_load_dwordx2 v[42:43], v[28:29], off offset:1024 nt
	global_load_dwordx2 v[44:45], v[16:17], off offset:1536 nt
	global_load_dwordx2 v[46:47], v[28:29], off nt
	global_load_dwordx2 v[56:57], v[16:17], off nt
	global_load_dword v58, v21, s[0:1]
	v_lshl_add_u64 v[16:17], v[24:25], 0, s[20:21]
	global_load_dwordx4 v[16:19], v[16:17], off
	s_cmpk_gt_i32 s12, 0x7fff
	s_waitcnt vmcnt(10)
	v_mov_b32_e32 v60, v31
	v_mov_b32_e32 v61, v32
	v_mov_b32_e32 v31, v33
	v_pk_add_f32 v[30:31], v[60:61], v[30:31]
	s_waitcnt vmcnt(8)
	v_and_b32_e32 v61, 0xffff0000, v36
	v_add_f32_e32 v30, v30, v31
	ds_bpermute_b32 v32, v20, v30
	v_and_b32_e32 v55, 0xffff0000, v35
	v_lshlrev_b32_e32 v59, 16, v35
	s_waitcnt vmcnt(4)
	v_lshlrev_b32_e32 v70, 16, v44
	v_and_b32_e32 v72, 0xffff0000, v44
	s_waitcnt lgkmcnt(0)
	v_add_f32_e32 v30, v30, v32
	ds_bpermute_b32 v32, v48, v30
	v_lshlrev_b32_e32 v74, 16, v45
	v_and_b32_e32 v76, 0xffff0000, v45
	s_waitcnt vmcnt(2)
	v_lshlrev_b32_e32 v44, 16, v57
	v_and_b32_e32 v45, 0xffff0000, v57
	s_waitcnt lgkmcnt(0)
	v_add_f32_e32 v30, v30, v32
	v_fmamk_f32 v30, v30, 0x3a800000, v53
	v_mul_f32_e32 v32, 0x4f800000, v30
	v_cmp_gt_f32_e32 vcc, s19, v30
	s_waitcnt vmcnt(1)
	v_mul_f32_e32 v57, v58, v55
	v_and_b32_e32 v31, 0xffff0000, v34
	v_cndmask_b32_e32 v30, v30, v32, vcc
	v_sqrt_f32_e32 v32, v30
	v_lshlrev_b32_e32 v33, 16, v34
	v_lshlrev_b32_e32 v35, 16, v36
	v_lshlrev_b32_e32 v34, 16, v38
	v_add_u32_e32 v55, -1, v32
	v_and_b32_e32 v60, 0xffff0000, v38
	v_lshlrev_b32_e32 v62, 16, v39
	v_and_b32_e32 v36, 0xffff0000, v39
	v_lshlrev_b32_e32 v39, 16, v40
	v_lshlrev_b32_e32 v38, 16, v42
	v_and_b32_e32 v65, 0xffff0000, v40
	v_and_b32_e32 v64, 0xffff0000, v42
	v_lshlrev_b32_e32 v66, 16, v43
	v_and_b32_e32 v40, 0xffff0000, v43
	v_lshlrev_b32_e32 v42, 16, v47
	v_and_b32_e32 v43, 0xffff0000, v47
	v_lshlrev_b32_e32 v68, 16, v46
	v_and_b32_e32 v69, 0xffff0000, v46
	v_lshlrev_b32_e32 v46, 16, v56
	v_and_b32_e32 v47, 0xffff0000, v56
	v_mul_f32_e32 v71, v58, v59
	v_add_u32_e32 v56, 1, v32
	v_fma_f32 v59, -v55, v32, v30
	v_fma_f32 v73, -v56, v32, v30
	v_cmp_ge_f32_e64 s[0:1], 0, v59
	v_lshlrev_b32_e32 v63, 16, v37
	v_and_b32_e32 v37, 0xffff0000, v37
	v_cndmask_b32_e64 v32, v32, v55, s[0:1]
	v_cmp_lt_f32_e64 s[0:1], 0, v73
	v_lshlrev_b32_e32 v67, 16, v41
	v_and_b32_e32 v41, 0xffff0000, v41
	v_cndmask_b32_e64 v32, v32, v56, s[0:1]
	v_mul_f32_e32 v55, 0x37800000, v32
	v_cndmask_b32_e32 v32, v32, v55, vcc
	v_cmp_class_f32_e32 vcc, v30, v54
	v_mov_b32_e32 v73, v58
	s_waitcnt vmcnt(0)
	v_add_f32_e32 v16, v16, v17
	v_cndmask_b32_e32 v30, v32, v30, vcc
	v_div_scale_f32 v32, s[0:1], v30, v30, 1.0
	v_rcp_f32_e32 v55, v32
	v_div_scale_f32 v56, vcc, 1.0, v30, 1.0
	v_add_f32_e32 v18, v18, v19
	v_fma_f32 v59, -v32, v55, 1.0
	v_fmac_f32_e32 v55, v59, v55
	v_mul_f32_e32 v59, v56, v55
	v_fma_f32 v75, -v32, v59, v56
	v_fmac_f32_e32 v59, v75, v55
	v_fma_f32 v32, -v32, v59, v56
	v_div_fmas_f32 v32, v32, v55, v59
	v_div_fixup_f32 v59, v32, v30, 1.0
	v_mov_b32_e32 v30, v59
	v_mul_f32_e32 v32, v59, v74
	v_pk_mul_f32 v[44:45], v[30:31], v[44:45] op_sel_hi:[0,1]
	v_pk_mul_f32 v[34:35], v[58:59], v[34:35]
	v_pk_mul_f32 v[60:61], v[58:59], v[60:61]
	v_pk_mul_f32 v[62:63], v[58:59], v[62:63]
	v_pk_mul_f32 v[36:37], v[58:59], v[36:37]
	v_pk_mul_f32 v[38:39], v[58:59], v[38:39]
	v_pk_mul_f32 v[64:65], v[58:59], v[64:65]
	v_pk_mul_f32 v[66:67], v[58:59], v[66:67]
	v_pk_mul_f32 v[40:41], v[58:59], v[40:41]
	v_mul_f32_e32 v75, v59, v70
	v_mul_f32_e32 v77, v59, v72
	v_mul_f32_e32 v55, v59, v76
	v_mul_f32_e32 v59, v2, v32
	v_pk_mul_f32 v[46:47], v[30:31], v[46:47] op_sel_hi:[0,1]
	v_pk_mul_f32 v[44:45], v[14:15], v[44:45]
	v_pk_mul_f32 v[46:47], v[12:13], v[46:47]
	v_pk_fma_f32 v[80:81], v[58:59], v[42:43], v[44:45] op_sel_hi:[0,1,1]
	v_pk_fma_f32 v[68:69], v[58:59], v[68:69], v[46:47] op_sel_hi:[0,1,1]
	v_pk_mov_b32 v[42:43], v[80:81], v[0:1] op_sel:[1,0]
	v_mov_b32_e32 v74, v81
	v_pk_mul_f32 v[42:43], v[42:43], v[74:75]
	v_pk_mov_b32 v[82:83], v[68:69], v[0:1] op_sel:[1,0]
	v_mov_b32_e32 v74, v69
	v_mov_b32_e32 v72, v80
	v_mov_b32_e32 v32, v80
	v_mov_b32_e32 v44, v68
	v_mov_b32_e32 v45, v58
	v_mov_b32_e32 v46, v68
	v_mov_b32_e32 v47, v33
	v_pk_mul_f32 v[74:75], v[82:83], v[74:75]
	v_pk_fma_f32 v[32:33], v[72:73], v[32:33], v[42:43]
	v_pk_fma_f32 v[72:73], v[44:45], v[46:47], v[74:75]
	v_mul_f32_e32 v79, v3, v55
	v_pk_add_f32 v[42:43], v[72:73], v[32:33]
	v_pk_mul_f32 v[32:33], v[72:73], v[32:33]
	v_add_f32_e32 v16, v16, v18
	v_mov_b32_e32 v43, v33
	v_mov_b32_e32 v32, v63
	v_mov_b32_e32 v33, v37
	v_mov_b32_e32 v63, v36
	v_mov_b32_e32 v36, v35
	v_mov_b32_e32 v37, v61
	v_mov_b32_e32 v35, v60
	v_pk_fma_f32 v[60:61], v[8:9], v[36:37], v[34:35]
	v_pk_fma_f32 v[62:63], v[10:11], v[32:33], v[62:63]
	v_mov_b32_e32 v36, v61
	v_mov_b32_e32 v37, v1
	v_mov_b32_e32 v76, v61
	v_mov_b32_e32 v32, v63
	v_mov_b32_e32 v33, v1
	v_mov_b32_e32 v34, v60
	v_mov_b32_e32 v35, v58
	v_mov_b32_e32 v30, v60
	v_pk_mul_f32 v[36:37], v[36:37], v[76:77]
	v_mov_b32_e32 v76, v63
	v_pk_fma_f32 v[74:75], v[34:35], v[30:31], v[36:37]
	v_mov_b32_e32 v34, v62
	v_mov_b32_e32 v30, v62
	v_pk_mul_f32 v[32:33], v[32:33], v[76:77]
	ds_bpermute_b32 v18, v20, v16
	v_pk_fma_f32 v[30:31], v[34:35], v[30:31], v[32:33]
	s_waitcnt lgkmcnt(0)
	v_add_f32_e32 v16, v16, v18
	v_pk_add_f32 v[32:33], v[74:75], v[30:31]
	v_pk_mul_f32 v[30:31], v[74:75], v[30:31]
	v_mov_b32_e32 v74, v73
	v_mov_b32_e32 v33, v31
	v_pk_add_f32 v[30:31], v[42:43], v[32:33]
	v_mov_b32_e32 v32, v67
	v_mov_b32_e32 v33, v41
	v_mov_b32_e32 v67, v40
	v_pk_fma_f32 v[66:67], v[6:7], v[32:33], v[66:67]
	s_nop 0
	v_mov_b32_e32 v78, v66
	v_mov_b32_e32 v56, v66
	v_pk_add_f32 v[56:57], v[78:79], v[56:57]
	v_mul_f32_e32 v32, v67, v67
	v_pk_fma_f32 v[32:33], v[66:67], v[66:67], v[32:33] op_sel_hi:[1,1,0]
	v_pk_mul_f32 v[34:35], v[56:57], v[56:57]
	s_nop 0
	v_mov_b32_e32 v33, v35
	v_mov_b32_e32 v34, v39
	v_mov_b32_e32 v35, v65
	v_mov_b32_e32 v39, v64
	v_pk_fma_f32 v[64:65], v[4:5], v[34:35], v[38:39]
	s_nop 0
	v_mov_b32_e32 v58, v64
	v_mov_b32_e32 v70, v64
	v_pk_add_f32 v[58:59], v[58:59], v[70:71]
	v_mul_f32_e32 v34, v65, v65
	v_pk_fma_f32 v[34:35], v[64:65], v[64:65], v[34:35] op_sel_hi:[1,1,0]
	v_pk_mul_f32 v[36:37], v[58:59], v[58:59]
	v_lshl_add_u64 v[70:71], v[26:27], 0, s[14:15]
	v_mov_b32_e32 v35, v37
	v_pk_add_f32 v[32:33], v[34:35], v[32:33]
	v_lshl_add_u64 v[34:35], v[22:23], 0, s[14:15]
	v_pk_add_f32 v[30:31], v[30:31], v[32:33]
	s_nop 0
	v_add_f32_e32 v31, v30, v31
	ds_bpermute_b32 v32, v20, v31
	global_load_dword v30, v21, s[16:17]
	s_waitcnt lgkmcnt(0)
	v_add_f32_e32 v31, v31, v32
	ds_bpermute_b32 v36, v48, v31
	global_load_dwordx2 v[32:33], v[34:35], off nt
	global_load_dwordx2 v[42:43], v[34:35], off offset:512 nt
	global_load_dwordx2 v[38:39], v[34:35], off offset:1024 nt
	global_load_dwordx2 v[46:47], v[34:35], off offset:1536 nt
	s_waitcnt lgkmcnt(0)
	v_add_f32_e32 v31, v31, v36
	global_load_dwordx2 v[34:35], v[70:71], off nt
	global_load_dwordx2 v[44:45], v[70:71], off offset:512 nt
	global_load_dwordx2 v[40:41], v[70:71], off offset:1024 nt
	global_load_dwordx2 v[36:37], v[70:71], off offset:1536 nt
	ds_bpermute_b32 v55, v49, v31
	s_waitcnt lgkmcnt(0)
	v_add_f32_e32 v31, v31, v55
	ds_bpermute_b32 v55, v50, v31
	s_waitcnt lgkmcnt(0)
	v_add_f32_e32 v31, v31, v55
	ds_bpermute_b32 v55, v51, v31
	s_waitcnt lgkmcnt(0)
	v_add_f32_e32 v31, v31, v55
	ds_bpermute_b32 v55, v52, v31
	s_waitcnt lgkmcnt(0)
	v_add_f32_e32 v17, v31, v55
	v_fmamk_f32 v17, v17, 0x3a800000, v53
	v_mul_f32_e32 v31, 0x4f800000, v17
	v_cmp_gt_f32_e32 vcc, s19, v17
	s_nop 1
	v_cndmask_b32_e32 v17, v17, v31, vcc
	v_sqrt_f32_e32 v31, v17
	s_nop 0
	v_add_u32_e32 v19, -1, v31
	v_fma_f32 v55, -v19, v31, v17
	v_cmp_ge_f32_e64 s[0:1], 0, v55
	v_add_u32_e32 v55, 1, v31
	s_nop 0
	v_cndmask_b32_e64 v19, v31, v19, s[0:1]
	v_fma_f32 v31, -v55, v31, v17
	v_cmp_lt_f32_e64 s[0:1], 0, v31
	s_nop 1
	v_cndmask_b32_e64 v19, v19, v55, s[0:1]
	v_mul_f32_e32 v31, 0x37800000, v19
	v_cndmask_b32_e32 v19, v19, v31, vcc
	v_cmp_class_f32_e32 vcc, v17, v54
	s_nop 1
	v_cndmask_b32_e32 v19, v19, v17, vcc
	v_div_scale_f32 v31, s[0:1], v19, v19, 1.0
	v_rcp_f32_e32 v55, v31
	ds_bpermute_b32 v17, v48, v16
	v_fma_f32 v18, -v31, v55, 1.0
	v_fmac_f32_e32 v55, v18, v55
	v_div_scale_f32 v18, vcc, 1.0, v19, 1.0
	v_mul_f32_e32 v56, v18, v55
	v_fma_f32 v58, -v31, v56, v18
	v_fmac_f32_e32 v56, v58, v55
	v_fma_f32 v18, -v31, v56, v18
	v_div_fmas_f32 v18, v18, v55, v56
	v_div_fixup_f32 v18, v18, v19, 1.0
	v_pk_mul_f32 v[60:61], v[18:19], v[60:61] op_sel_hi:[0,1]
	v_pk_mul_f32 v[62:63], v[18:19], v[62:63] op_sel_hi:[0,1]
	v_cvt_pk_bf16_f32 v60, v60, v61
	v_cvt_pk_bf16_f32 v61, v62, v63
	global_store_dwordx2 v[28:29], v[60:61], off offset:512 sc1 nt
	v_pk_mul_f32 v[60:61], v[18:19], v[64:65] op_sel_hi:[0,1]
	v_pk_mul_f32 v[62:63], v[18:19], v[66:67] op_sel_hi:[0,1]
	v_cvt_pk_bf16_f32 v60, v60, v61
	v_cvt_pk_bf16_f32 v61, v62, v63
	v_mov_b32_e32 v56, v59
	v_pk_mul_f32 v[68:69], v[18:19], v[68:69] op_sel_hi:[0,1]
	v_pk_mul_f32 v[70:71], v[18:19], v[80:81] op_sel_hi:[0,1]
	global_store_dwordx2 v[28:29], v[60:61], off offset:1024 sc1 nt
	v_pk_mul_f32 v[60:61], v[18:19], v[74:75] op_sel_hi:[0,1]
	v_pk_mul_f32 v[18:19], v[18:19], v[56:57] op_sel_hi:[0,1]
	v_cvt_pk_bf16_f32 v68, v68, v69
	v_cvt_pk_bf16_f32 v69, v70, v71
	v_cvt_pk_bf16_f32 v58, v60, v61
	v_cvt_pk_bf16_f32 v59, v18, v19
	global_store_dwordx2 v[28:29], v[68:69], off sc1 nt
	global_store_dwordx2 v[28:29], v[58:59], off offset:1536 sc1 nt
	s_cbranch_scc1 .LBB0_806
	s_waitcnt lgkmcnt(0)
	v_add_f32_e32 v16, v16, v17
	v_fmamk_f32 v16, v16, 0x3a800000, v53
	v_mul_f32_e32 v17, 0x4f800000, v16
	v_cmp_gt_f32_e32 vcc, s19, v16
	s_waitcnt vmcnt(8)
	v_lshlrev_b32_e32 v19, 16, v47
	s_waitcnt vmcnt(6)
	v_lshlrev_b32_e32 v57, 16, v44
	v_cndmask_b32_e32 v16, v16, v17, vcc
	v_sqrt_f32_e32 v18, v16
	v_and_b32_e32 v17, 0xffff0000, v47
	v_lshlrev_b32_e32 v47, 16, v46
	v_and_b32_e32 v59, 0xffff0000, v44
	v_add_u32_e32 v28, -1, v18
	v_fma_f32 v29, -v28, v18, v16
	v_cmp_ge_f32_e64 s[0:1], 0, v29
	v_add_u32_e32 v29, 1, v18
	v_lshlrev_b32_e32 v61, 16, v45
	v_cndmask_b32_e64 v28, v18, v28, s[0:1]
	v_fma_f32 v18, -v29, v18, v16
	v_cmp_lt_f32_e64 s[0:1], 0, v18
	v_and_b32_e32 v45, 0xffff0000, v45
	v_and_b32_e32 v44, 0xffff0000, v43
	v_cndmask_b32_e64 v18, v28, v29, s[0:1]
	v_mul_f32_e32 v28, 0x37800000, v18
	v_cndmask_b32_e32 v18, v18, v28, vcc
	v_cmp_class_f32_e32 vcc, v16, v54
	v_and_b32_e32 v29, 0xffff0000, v46
	v_lshlrev_b32_e32 v56, 16, v42
	v_cndmask_b32_e32 v16, v18, v16, vcc
	v_div_scale_f32 v18, s[0:1], v16, v16, 1.0
	v_rcp_f32_e32 v28, v18
	v_and_b32_e32 v58, 0xffff0000, v42
	v_lshlrev_b32_e32 v60, 16, v43
	s_waitcnt vmcnt(5)
	v_and_b32_e32 v63, 0xffff0000, v40
	v_fma_f32 v31, -v18, v28, 1.0
	v_fmac_f32_e32 v28, v31, v28
	v_div_scale_f32 v31, vcc, 1.0, v16, 1.0
	v_mul_f32_e32 v46, v31, v28
	v_fma_f32 v55, -v18, v46, v31
	v_fmac_f32_e32 v46, v55, v28
	v_fma_f32 v18, -v18, v46, v31
	v_div_fmas_f32 v18, v18, v28, v46
	v_div_fixup_f32 v31, v18, v16, 1.0
	v_pk_mul_f32 v[42:43], v[30:31], v[44:45]
	v_lshlrev_b32_e32 v45, 16, v40
	v_lshlrev_b32_e32 v65, 16, v41
	v_and_b32_e32 v41, 0xffff0000, v41
	v_and_b32_e32 v40, 0xffff0000, v39
	s_waitcnt vmcnt(4)
	v_lshlrev_b32_e32 v16, 16, v36
	v_lshlrev_b32_e32 v44, 16, v38
	v_and_b32_e32 v62, 0xffff0000, v38
	v_lshlrev_b32_e32 v64, 16, v39
	v_pk_mul_f32 v[38:39], v[30:31], v[40:41]
	v_mul_f32_e32 v41, v31, v16
	v_and_b32_e32 v16, 0xffff0000, v36
	v_mul_f32_e32 v67, v31, v16
	v_lshlrev_b32_e32 v16, 16, v37
	v_mul_f32_e32 v16, v31, v16
	v_mul_f32_e32 v69, v2, v16
	v_and_b32_e32 v16, 0xffff0000, v37
	v_mul_f32_e32 v16, v31, v16
	v_mul_f32_e32 v17, v30, v17
	v_mul_f32_e32 v37, v3, v16
	v_lshlrev_b32_e32 v72, 16, v35
	v_and_b32_e32 v73, 0xffff0000, v35
	v_mov_b32_e32 v16, v31
	v_pk_mul_f32 v[72:73], v[16:17], v[72:73] op_sel_hi:[0,1]
	v_lshlrev_b32_e32 v70, 16, v33
	v_and_b32_e32 v71, 0xffff0000, v33
	v_pk_mul_f32 v[72:73], v[14:15], v[72:73]
	v_and_b32_e32 v33, 0xffff0000, v34
	v_pk_fma_f32 v[70:71], v[30:31], v[70:71], v[72:73] op_sel_hi:[0,1,1]
	v_lshlrev_b32_e32 v72, 16, v32
	v_and_b32_e32 v73, 0xffff0000, v32
	v_lshlrev_b32_e32 v32, 16, v34
	v_pk_mul_f32 v[32:33], v[16:17], v[32:33] op_sel_hi:[0,1]
	v_pk_mul_f32 v[32:33], v[12:13], v[32:33]
	v_mov_b32_e32 v40, v71
	v_pk_fma_f32 v[32:33], v[30:31], v[72:73], v[32:33] op_sel_hi:[0,1,1]
	v_pk_mov_b32 v[72:73], v[70:71], v[0:1] op_sel:[1,0]
	v_pk_mov_b32 v[78:79], v[32:33], v[0:1] op_sel:[1,0]
	v_pk_mul_f32 v[72:73], v[72:73], v[40:41]
	v_mov_b32_e32 v40, v33
	v_mov_b32_e32 v34, v70
	v_mov_b32_e32 v35, v30
	v_mov_b32_e32 v46, v70
	v_mov_b32_e32 v74, v32
	v_mov_b32_e32 v75, v30
	v_mov_b32_e32 v76, v32
	v_mov_b32_e32 v77, v47
	v_pk_mul_f32 v[40:41], v[78:79], v[40:41]
	v_pk_fma_f32 v[34:35], v[34:35], v[46:47], v[72:73]
	v_pk_fma_f32 v[40:41], v[74:75], v[76:77], v[40:41]
	v_pk_mul_f32 v[60:61], v[30:31], v[60:61]
	v_pk_add_f32 v[46:47], v[40:41], v[34:35]
	v_pk_mul_f32 v[34:35], v[40:41], v[34:35]
	v_pk_mul_f32 v[56:57], v[30:31], v[56:57]
	v_pk_mul_f32 v[58:59], v[30:31], v[58:59]
	v_mov_b32_e32 v47, v35
	v_mov_b32_e32 v34, v61
	v_mov_b32_e32 v35, v43
	v_mov_b32_e32 v61, v42
	v_pk_fma_f32 v[34:35], v[10:11], v[34:35], v[60:61]
	v_mov_b32_e32 v60, v57
	v_mov_b32_e32 v61, v59
	v_mov_b32_e32 v57, v58
	v_pk_fma_f32 v[56:57], v[8:9], v[60:61], v[56:57]
	v_mov_b32_e32 v61, v1
	v_mov_b32_e32 v60, v57
	v_mov_b32_e32 v66, v57
	v_mov_b32_e32 v42, v35
	v_mov_b32_e32 v43, v1
	v_mov_b32_e32 v58, v56
	v_mov_b32_e32 v59, v30
	v_mov_b32_e32 v28, v56
	v_pk_mul_f32 v[60:61], v[60:61], v[66:67]
	v_mov_b32_e32 v66, v35
	v_mul_f32_e32 v19, v30, v19
	v_pk_mul_f32 v[44:45], v[30:31], v[44:45]
	v_pk_mul_f32 v[62:63], v[30:31], v[62:63]
	v_pk_mul_f32 v[64:65], v[30:31], v[64:65]
	v_pk_fma_f32 v[58:59], v[58:59], v[28:29], v[60:61]
	v_mov_b32_e32 v60, v34
	v_mov_b32_e32 v61, v30
	v_mov_b32_e32 v28, v34
	v_pk_mul_f32 v[30:31], v[42:43], v[66:67]
	s_ashr_i32 s13, s12, 31
	v_pk_fma_f32 v[28:29], v[60:61], v[28:29], v[30:31]
	s_nop 0
	v_pk_add_f32 v[30:31], v[58:59], v[28:29]
	v_pk_mul_f32 v[28:29], v[58:59], v[28:29]
	v_mov_b32_e32 v58, v41
	v_mov_b32_e32 v31, v29
	v_pk_add_f32 v[28:29], v[46:47], v[30:31]
	v_mov_b32_e32 v30, v65
	v_mov_b32_e32 v31, v39
	v_mov_b32_e32 v65, v38
	v_pk_fma_f32 v[30:31], v[6:7], v[30:31], v[64:65]
	s_nop 0
	v_mov_b32_e32 v36, v30
	v_mov_b32_e32 v16, v30
	v_pk_add_f32 v[16:17], v[36:37], v[16:17]
	v_mul_f32_e32 v18, v31, v31
	v_pk_fma_f32 v[36:37], v[30:31], v[30:31], v[18:19] op_sel_hi:[1,1,0]
	v_pk_mul_f32 v[38:39], v[16:17], v[16:17]
	s_nop 0
	v_mov_b32_e32 v37, v39
	v_mov_b32_e32 v38, v45
	v_mov_b32_e32 v39, v63
	v_mov_b32_e32 v45, v62
	v_pk_fma_f32 v[38:39], v[4:5], v[38:39], v[44:45]
	s_nop 0
	v_mov_b32_e32 v68, v38
	v_mov_b32_e32 v18, v38
	v_pk_add_f32 v[18:19], v[68:69], v[18:19]
	v_mul_f32_e32 v16, v39, v39
	v_pk_fma_f32 v[42:43], v[38:39], v[38:39], v[16:17] op_sel_hi:[1,1,0]
	v_pk_mul_f32 v[44:45], v[18:19], v[18:19]
	s_nop 0
	v_mov_b32_e32 v43, v45
	v_pk_add_f32 v[36:37], v[42:43], v[36:37]
	s_nop 0
	v_pk_add_f32 v[28:29], v[28:29], v[36:37]
	s_nop 0
	v_add_f32_e32 v16, v28, v29
	ds_bpermute_b32 v18, v20, v16
	s_waitcnt lgkmcnt(0)
	v_add_f32_e32 v16, v16, v18
	ds_bpermute_b32 v18, v48, v16
	s_waitcnt lgkmcnt(0)
	v_add_f32_e32 v16, v16, v18
	ds_bpermute_b32 v18, v49, v16
	s_waitcnt lgkmcnt(0)
	v_add_f32_e32 v16, v16, v18
	ds_bpermute_b32 v18, v50, v16
	s_waitcnt lgkmcnt(0)
	v_add_f32_e32 v16, v16, v18
	ds_bpermute_b32 v18, v51, v16
	s_waitcnt lgkmcnt(0)
	v_add_f32_e32 v16, v16, v18
	ds_bpermute_b32 v18, v52, v16
	s_waitcnt lgkmcnt(0)
	v_add_f32_e32 v16, v16, v18
	v_fmamk_f32 v16, v16, 0x3a800000, v53
	v_mul_f32_e32 v18, 0x4f800000, v16
	v_cmp_gt_f32_e32 vcc, s19, v16
	s_nop 1
	v_cndmask_b32_e32 v16, v16, v18, vcc
	v_sqrt_f32_e32 v18, v16
	s_nop 0
	v_add_u32_e32 v28, -1, v18
	v_fma_f32 v29, -v28, v18, v16
	v_cmp_ge_f32_e64 s[0:1], 0, v29
	v_add_u32_e32 v29, 1, v18
	s_nop 0
	v_cndmask_b32_e64 v28, v18, v28, s[0:1]
	v_fma_f32 v18, -v29, v18, v16
	v_cmp_lt_f32_e64 s[0:1], 0, v18
	s_nop 1
	v_cndmask_b32_e64 v18, v28, v29, s[0:1]
	v_mul_f32_e32 v28, 0x37800000, v18
	v_cndmask_b32_e32 v18, v18, v28, vcc
	v_cmp_class_f32_e32 vcc, v16, v54
	s_nop 1
	v_cndmask_b32_e32 v16, v18, v16, vcc
	v_div_scale_f32 v18, s[0:1], v16, v16, 1.0
	v_rcp_f32_e32 v36, v18
	s_lshl_b64 s[0:1], s[12:13], 11
	v_lshl_add_u64 v[28:29], v[22:23], 0, s[0:1]
	v_fma_f32 v37, -v18, v36, 1.0
	v_fmac_f32_e32 v36, v37, v36
	v_div_scale_f32 v37, vcc, 1.0, v16, 1.0
	v_mul_f32_e32 v40, v37, v36
	v_fma_f32 v42, -v18, v40, v37
	v_fmac_f32_e32 v40, v42, v36
	v_fma_f32 v18, -v18, v40, v37
	v_div_fmas_f32 v18, v18, v36, v40
	v_div_fixup_f32 v18, v18, v16, 1.0
	v_pk_mul_f32 v[32:33], v[18:19], v[32:33] op_sel_hi:[0,1]
	v_pk_mul_f32 v[36:37], v[18:19], v[70:71] op_sel_hi:[0,1]
	v_cvt_pk_bf16_f32 v32, v32, v33
	v_cvt_pk_bf16_f32 v33, v36, v37
	global_store_dwordx2 v[28:29], v[32:33], off sc1 nt
	v_pk_mul_f32 v[32:33], v[18:19], v[56:57] op_sel_hi:[0,1]
	v_pk_mul_f32 v[34:35], v[18:19], v[34:35] op_sel_hi:[0,1]
	v_cvt_pk_bf16_f32 v32, v32, v33
	v_cvt_pk_bf16_f32 v33, v34, v35
	global_store_dwordx2 v[28:29], v[32:33], off offset:512 sc1 nt
	v_pk_mul_f32 v[32:33], v[18:19], v[38:39] op_sel_hi:[0,1]
	v_pk_mul_f32 v[30:31], v[18:19], v[30:31] op_sel_hi:[0,1]
	v_mov_b32_e32 v16, v19
	v_cvt_pk_bf16_f32 v32, v32, v33
	v_cvt_pk_bf16_f32 v33, v30, v31
	v_pk_mul_f32 v[30:31], v[18:19], v[58:59] op_sel_hi:[0,1]
	v_pk_mul_f32 v[16:17], v[18:19], v[16:17] op_sel_hi:[0,1]
	v_cvt_pk_bf16_f32 v30, v30, v31
	v_cvt_pk_bf16_f32 v31, v16, v17
	global_store_dwordx2 v[28:29], v[32:33], off offset:1024 sc1 nt
	global_store_dwordx2 v[28:29], v[30:31], off offset:1536 sc1 nt
	s_branch .LBB0_806
